# attention output stores device-scope
# baseline (speedup 1.0000x reference)
; #define LAS __attribute__((address_space(3)))
; __device__ __forceinline__ void store4bf(bf16_t* p, f32x4 v) { u32x2 w; w.x = cvt_pk_bf16(v[0], v[1]); w.y = cvt_pk_bf16(v[2], v[3]); *(u32x2*)p = w; }
; __device__ __forceinline__ float sum32(float v) { return v + xhalf(v); }
; template <int MODE>
; __device__ __forceinline__ void attn_item(const Params& P, int layer, int b, int h, int map, int qb) {
;     ...
;   const float la = sum32(sa.l), ia = 1.0f / la;
;   if (qvalid) {
;     const int row = meta ? NREAL + 16 * b + e_q : b * SEQ + (e_q - 64);
;     if (MODE == 1) {
;     } else {
;       const int ycol = MODE == 0 ? h * 64 : 640 + h * 64;
;       bf16_t* yp = (bf16_t*)(ws + WS_HN) + (size_t)row * DM + ycol + 4 * hh;
; #pragma unroll
;       for (int g = 0; g < 4; ++g) {
;         store4bf(yp + 8 * g, (f32x4){sa.o0[4 * g] * ia, sa.o0[4 * g + 1] * ia, sa.o0[4 * g + 2] * ia, sa.o0[4 * g + 3] * ia});
;         store4bf(yp + 32 + 8 * g, (f32x4){sa.o1[4 * g] * ia, sa.o1[4 * g + 1] * ia, sa.o1[4 * g + 2] * ia, sa.o1[4 * g + 3] * ia});
;       }
;     }
;   }
;   if (MODE == 1) {
;     LAS float* stash = (LAS float*)(lds + 4 * KBUF + 4 * VBUF + 1024) + (size_t)w * 32 * 64 + lane;
;     if (map == 0) {
; #pragma unroll
;       for (int i = 0; i < 16; ++i) { stash[i * 64] = sa.o0[i] * ia; stash[(16 + i) * 64] = sa.o1[i] * ia; }
;     } else {
;       const float lam = ((const float*)(ws + WS_CTL))[8 + layer], li = layer == 0 ? 0.2f : 0.35550906f, ib = lam * ia;
;       f32x16 y0, y1; float ss = 0.f;
; #pragma unroll
;       for (int i = 0; i < 16; ++i) { y0[i] = stash[i * 64] - sa.o0[i] * ib; y1[i] = stash[(16 + i) * 64] - sa.o1[i] * ib; ss += y0[i] * y0[i] + y1[i] * y1[i]; }
;       ss = sum32(ss);
.LBB0_1288:
	v_mov_b32_e32 v34, v210
	s_lshl_b32 s2, s21, 13
	v_lshlrev_b32_e32 v34, 2, v34
	v_xor_b32_e32 v34, 0x80, v34
	ds_bpermute_b32 v34, v34, v228
	s_add_i32 s4, s2, 0
	v_lshl_add_u32 v69, v167, 2, s4
	s_cmp_lg_u32 s75, 0
	v_add_u32_e32 v71, 0xe400, v69
	s_waitcnt lgkmcnt(0)
	v_add_f32_e32 v34, v228, v34
	v_div_scale_f32 v35, s[2:3], v34, v34, 1.0
	v_rcp_f32_e32 v36, v35
	v_div_scale_f32 v37, vcc, 1.0, v34, 1.0
	v_fma_f32 v38, -v35, v36, 1.0
	v_fmac_f32_e32 v36, v38, v36
	v_mul_f32_e32 v38, v37, v36
	v_fma_f32 v39, -v35, v38, v37
	v_fmac_f32_e32 v38, v39, v36
	v_fma_f32 v35, -v35, v38, v37
	v_div_fmas_f32 v35, v35, v36, v38
	v_div_fixup_f32 v70, v35, v34, 1.0
	s_cbranch_scc0 .LBB0_1324
	global_load_dword v34, v1, s[52:53] offset:32
	s_waitcnt vmcnt(0)
	v_mul_f32_e32 v54, v70, v34
	ds_read2st64_b32 v[34:35], v69 offset0:228 offset1:229
	ds_read2st64_b32 v[36:37], v69 offset0:244 offset1:245
	s_waitcnt lgkmcnt(1)
	v_pk_fma_f32 v[62:63], v[18:19], v[54:55], v[34:35] op_sel_hi:[1,0,1] neg_lo:[1,0,0] neg_hi:[1,0,0]
	s_waitcnt lgkmcnt(0)
	v_pk_fma_f32 v[36:37], v[2:3], v[54:55], v[36:37] op_sel_hi:[1,0,1] neg_lo:[1,0,0] neg_hi:[1,0,0]
	s_nop 0
	v_pk_mul_f32 v[34:35], v[36:37], v[36:37]
	s_nop 0
	v_pk_fma_f32 v[66:67], v[62:63], v[62:63], v[34:35]
	ds_read2st64_b32 v[34:35], v69 offset0:230 offset1:231
	ds_read2st64_b32 v[38:39], v69 offset0:246 offset1:247
	v_add_f32_e32 v66, v66, v67
	v_mov_b32_e32 v67, v210
	s_waitcnt lgkmcnt(1)
	v_pk_fma_f32 v[64:65], v[20:21], v[54:55], v[34:35] op_sel_hi:[1,0,1] neg_lo:[1,0,0] neg_hi:[1,0,0]
	s_waitcnt lgkmcnt(0)
	v_pk_fma_f32 v[42:43], v[4:5], v[54:55], v[38:39] op_sel_hi:[1,0,1] neg_lo:[1,0,0] neg_hi:[1,0,0]
	s_nop 0
	v_pk_mul_f32 v[34:35], v[42:43], v[42:43]
	s_nop 0
	v_pk_fma_f32 v[72:73], v[64:65], v[64:65], v[34:35]
	ds_read2st64_b32 v[34:35], v69 offset0:232 offset1:233
	ds_read2st64_b32 v[38:39], v69 offset0:248 offset1:249
	v_add_f32_e32 v66, v66, v72
	v_add_f32_e32 v66, v66, v73
	s_waitcnt lgkmcnt(1)
	v_pk_fma_f32 v[44:45], v[22:23], v[54:55], v[34:35] op_sel_hi:[1,0,1] neg_lo:[1,0,0] neg_hi:[1,0,0]
	s_waitcnt lgkmcnt(0)
	v_pk_fma_f32 v[34:35], v[6:7], v[54:55], v[38:39] op_sel_hi:[1,0,1] neg_lo:[1,0,0] neg_hi:[1,0,0]
	s_nop 0
	v_pk_mul_f32 v[38:39], v[34:35], v[34:35]
	s_nop 0
	v_pk_fma_f32 v[74:75], v[44:45], v[44:45], v[38:39]
	ds_read2st64_b32 v[38:39], v69 offset0:234 offset1:235
	ds_read2st64_b32 v[40:41], v69 offset0:250 offset1:251
	v_add_f32_e32 v66, v66, v74
	v_add_f32_e32 v66, v66, v75
	s_waitcnt lgkmcnt(1)
	v_pk_fma_f32 v[56:57], v[24:25], v[54:55], v[38:39] op_sel_hi:[1,0,1] neg_lo:[1,0,0] neg_hi:[1,0,0]
	s_waitcnt lgkmcnt(0)
	v_pk_fma_f32 v[46:47], v[8:9], v[54:55], v[40:41] op_sel_hi:[1,0,1] neg_lo:[1,0,0] neg_hi:[1,0,0]
	s_nop 0
	v_pk_mul_f32 v[38:39], v[46:47], v[46:47]
	s_nop 0
	v_pk_fma_f32 v[76:77], v[56:57], v[56:57], v[38:39]
	ds_read2st64_b32 v[38:39], v69 offset0:236 offset1:237
	ds_read2st64_b32 v[40:41], v69 offset0:252 offset1:253
	v_add_f32_e32 v66, v66, v76
	v_add_f32_e32 v66, v66, v77
	s_waitcnt lgkmcnt(1)
	v_pk_fma_f32 v[48:49], v[26:27], v[54:55], v[38:39] op_sel_hi:[1,0,1] neg_lo:[1,0,0] neg_hi:[1,0,0]
	s_waitcnt lgkmcnt(0)
	v_pk_fma_f32 v[38:39], v[10:11], v[54:55], v[40:41] op_sel_hi:[1,0,1] neg_lo:[1,0,0] neg_hi:[1,0,0]
	s_nop 0
	v_pk_mul_f32 v[40:41], v[38:39], v[38:39]
	s_nop 0
	v_pk_fma_f32 v[78:79], v[48:49], v[48:49], v[40:41]
	ds_read2st64_b32 v[40:41], v69 offset0:238 offset1:239
	ds_read2st64_b32 v[50:51], v69 offset0:254 offset1:255
	v_add_f32_e32 v66, v66, v78
	v_add_f32_e32 v66, v66, v79
	s_waitcnt lgkmcnt(1)
	v_pk_fma_f32 v[58:59], v[28:29], v[54:55], v[40:41] op_sel_hi:[1,0,1] neg_lo:[1,0,0] neg_hi:[1,0,0]
	s_waitcnt lgkmcnt(0)
	v_pk_fma_f32 v[50:51], v[12:13], v[54:55], v[50:51] op_sel_hi:[1,0,1] neg_lo:[1,0,0] neg_hi:[1,0,0]
	s_nop 0
	v_pk_mul_f32 v[40:41], v[50:51], v[50:51]
	s_nop 0
	v_pk_fma_f32 v[80:81], v[58:59], v[58:59], v[40:41]
	ds_read2st64_b32 v[40:41], v69 offset0:240 offset1:241
	ds_read2st64_b32 v[60:61], v71 offset0:28 offset1:29
	v_add_f32_e32 v66, v66, v80
	v_add_f32_e32 v66, v66, v81
	s_waitcnt lgkmcnt(1)
	v_pk_fma_f32 v[52:53], v[30:31], v[54:55], v[40:41] op_sel_hi:[1,0,1] neg_lo:[1,0,0] neg_hi:[1,0,0]
	s_waitcnt lgkmcnt(0)
	v_pk_fma_f32 v[40:41], v[14:15], v[54:55], v[60:61] op_sel_hi:[1,0,1] neg_lo:[1,0,0] neg_hi:[1,0,0]
	s_nop 0
	v_pk_mul_f32 v[60:61], v[40:41], v[40:41]
	s_nop 0
	v_pk_fma_f32 v[82:83], v[52:53], v[52:53], v[60:61]
	ds_read2st64_b32 v[60:61], v69 offset0:242 offset1:243
	ds_read2st64_b32 v[84:85], v71 offset0:30 offset1:31
	v_add_f32_e32 v66, v66, v82
	v_add_f32_e32 v66, v66, v83
	s_waitcnt lgkmcnt(1)
	v_pk_fma_f32 v[60:61], v[32:33], v[54:55], v[60:61] op_sel_hi:[1,0,1] neg_lo:[1,0,0] neg_hi:[1,0,0]
	s_waitcnt lgkmcnt(0)
	v_pk_fma_f32 v[54:55], v[16:17], v[54:55], v[84:85] op_sel_hi:[1,0,1] neg_lo:[1,0,0] neg_hi:[1,0,0]
	v_lshlrev_b32_e32 v67, 2, v67
	v_pk_mul_f32 v[84:85], v[54:55], v[54:55]
	v_xor_b32_e32 v67, 0x80, v67
	v_pk_fma_f32 v[84:85], v[60:61], v[60:61], v[84:85]
	s_nop 0
	v_add_f32_e32 v66, v66, v84
	v_add_f32_e32 v66, v66, v85
	ds_bpermute_b32 v67, v67, v66
	s_and_saveexec_b64 s[2:3], s[24:25]
	s_cbranch_execz .LBB0_1291
; __device__ __forceinline__ void store4bf(bf16_t* p, f32x4 v) { u32x2 w; w.x = cvt_pk_bf16(v[0], v[1]); w.y = cvt_pk_bf16(v[2], v[3]); *(u32x2*)p = w; }
; __device__ __forceinline__ float sum32(float v) { return v + xhalf(v); }
; template <int MODE>
; __device__ __forceinline__ void attn_item(const Params& P, int layer, int b, int h, int map, int qb) {
;     ...
;       ss = sum32(ss);
;       const float rs = rsqrtf(ss * (1.0f / 64.0f) + 1e-6f) * (1.0f - li);
;       const float* sg = P.subln + layer * 64 + 4 * hh;
;       if (qvalid) {
;         const int row = meta ? NREAL + 16 * b + e_q : b * SEQ + (e_q - 64);
;         bf16_t* yp = (bf16_t*)(ws + WS_HN) + (size_t)row * DM + 384 + h * 64 + 4 * hh;
; #pragma unroll
;         for (int g = 0; g < 4; ++g) {
;           const f32x4 g0 = *(const f32x4*)(sg + 8 * g), g1 = *(const f32x4*)(sg + 32 + 8 * g);
;           store4bf(yp + 8 * g, (f32x4){y0[4 * g] * rs * g0[0], y0[4 * g + 1] * rs * g0[1], y0[4 * g + 2] * rs * g0[2], y0[4 * g + 3] * rs * g0[3]});
;           store4bf(yp + 32 + 8 * g, (f32x4){y1[4 * g] * rs * g1[0], y1[4 * g + 1] * rs * g1[1], y1[4 * g + 2] * rs * g1[2], y1[4 * g + 3] * rs * g1[3]});
;         }
;       }
	global_load_dwordx4 v[72:75], v0, s[56:57]
	global_load_dwordx4 v[76:79], v0, s[56:57] offset:128
	s_waitcnt lgkmcnt(0)
	v_add_f32_e32 v66, v66, v67
	v_fmamk_f32 v66, v66, 0x3c800000, v154
	v_cmp_gt_f32_e32 vcc, s46, v66
	v_mul_f32_e32 v67, 0x4b800000, v66
	v_readlane_b32 s24, v253, 16
	v_cndmask_b32_e32 v66, v66, v67, vcc
	v_rsq_f32_e32 v66, v66
	v_readlane_b32 s30, v253, 22
	v_readlane_b32 s31, v253, 23
	s_mov_b32 s67, s91
	v_mul_f32_e32 v67, 0x45800000, v66
	v_cndmask_b32_e32 v66, v66, v67, vcc
	v_mul_f32_e32 v68, v220, v66
	v_add_u32_e32 v66, s74, v166
	v_ashrrev_i32_e32 v67, 31, v66
	v_lshlrev_b64 v[66:67], 11, v[66:67]
	v_lshl_add_u64 v[66:67], s[30:31], 0, v[66:67]
	v_lshl_add_u64 v[66:67], v[66:67], 0, s[66:67]
	v_mov_b32_e32 v169, v1
	v_pk_mul_f32 v[62:63], v[62:63], v[68:69] op_sel_hi:[1,0]
	v_pk_mul_f32 v[64:65], v[64:65], v[68:69] op_sel_hi:[1,0]
	v_lshl_add_u64 v[80:81], v[66:67], 0, v[168:169]
	v_pk_mul_f32 v[36:37], v[36:37], v[68:69] op_sel_hi:[1,0]
	v_pk_mul_f32 v[42:43], v[42:43], v[68:69] op_sel_hi:[1,0]
	s_mov_b64 s[4:5], 0xb082300
	v_lshl_add_u64 v[66:67], v[80:81], 0, s[4:5]
	v_pk_mul_f32 v[34:35], v[34:35], v[68:69] op_sel_hi:[1,0]
	v_readlane_b32 s25, v253, 17
	v_readlane_b32 s26, v253, 18
	v_readlane_b32 s27, v253, 19
	v_readlane_b32 s28, v253, 20
	v_readlane_b32 s29, v253, 21
	s_waitcnt vmcnt(1)
	v_pk_mul_f32 v[62:63], v[62:63], v[72:73]
	v_pk_mul_f32 v[64:65], v[64:65], v[74:75]
	v_cvt_pk_bf16_f32 v62, v62, v63
	v_cvt_pk_bf16_f32 v63, v64, v65
	v_add_co_u32_e32 v64, vcc, s88, v80
	s_waitcnt vmcnt(0)
	v_pk_mul_f32 v[36:37], v[36:37], v[76:77]
	v_pk_mul_f32 v[42:43], v[42:43], v[78:79]
	v_addc_co_u32_e32 v65, vcc, 0, v81, vcc
	v_cvt_pk_bf16_f32 v36, v36, v37
	v_cvt_pk_bf16_f32 v37, v42, v43
	global_store_dwordx2 v[64:65], v[62:63], off offset:768 sc1
	global_store_dwordx2 v[66:67], v[36:37], off offset:64 sc1
	global_load_dwordx4 v[62:65], v0, s[56:57] offset:32
	s_nop 0
	global_load_dwordx4 v[72:75], v0, s[56:57] offset:160
	v_pk_mul_f32 v[36:37], v[44:45], v[68:69] op_sel_hi:[1,0]
	v_pk_mul_f32 v[42:43], v[56:57], v[68:69] op_sel_hi:[1,0]
	s_waitcnt vmcnt(1)
	v_pk_mul_f32 v[36:37], v[36:37], v[62:63]
	v_pk_mul_f32 v[42:43], v[42:43], v[64:65]
	v_cvt_pk_bf16_f32 v36, v36, v37
	v_cvt_pk_bf16_f32 v37, v42, v43
	global_store_dwordx2 v[66:67], v[36:37], off offset:16 sc1
	v_pk_mul_f32 v[36:37], v[46:47], v[68:69] op_sel_hi:[1,0]
	s_waitcnt vmcnt(1)
	v_pk_mul_f32 v[34:35], v[34:35], v[72:73]
	v_pk_mul_f32 v[36:37], v[36:37], v[74:75]
	v_cvt_pk_bf16_f32 v34, v34, v35
	v_cvt_pk_bf16_f32 v35, v36, v37
	global_store_dwordx2 v[66:67], v[34:35], off offset:80 sc1
	global_load_dwordx4 v[34:37], v0, s[56:57] offset:64
	s_nop 0
	global_load_dwordx4 v[42:45], v0, s[56:57] offset:192
	v_pk_mul_f32 v[46:47], v[48:49], v[68:69] op_sel_hi:[1,0]
	s_waitcnt vmcnt(1)
	v_pk_mul_f32 v[34:35], v[46:47], v[34:35]
	v_pk_mul_f32 v[46:47], v[58:59], v[68:69] op_sel_hi:[1,0]
	v_cvt_pk_bf16_f32 v34, v34, v35
	v_pk_mul_f32 v[36:37], v[46:47], v[36:37]
	s_nop 0
	v_cvt_pk_bf16_f32 v35, v36, v37
	global_store_dwordx2 v[66:67], v[34:35], off offset:32 sc1
	v_pk_mul_f32 v[34:35], v[38:39], v[68:69] op_sel_hi:[1,0]
	v_pk_mul_f32 v[36:37], v[50:51], v[68:69] op_sel_hi:[1,0]
	s_waitcnt vmcnt(1)
	v_pk_mul_f32 v[34:35], v[34:35], v[42:43]
	v_pk_mul_f32 v[36:37], v[36:37], v[44:45]
	v_cvt_pk_bf16_f32 v34, v34, v35
	v_cvt_pk_bf16_f32 v35, v36, v37
	global_store_dwordx2 v[66:67], v[34:35], off offset:96 sc1
	global_load_dwordx4 v[34:37], v0, s[56:57] offset:96
	s_nop 0
	global_load_dwordx4 v[42:45], v0, s[56:57] offset:224
	v_pk_mul_f32 v[38:39], v[52:53], v[68:69] op_sel_hi:[1,0]
	s_waitcnt vmcnt(1)
	v_pk_mul_f32 v[34:35], v[38:39], v[34:35]
	v_pk_mul_f32 v[38:39], v[60:61], v[68:69] op_sel_hi:[1,0]
	v_cvt_pk_bf16_f32 v34, v34, v35
	v_pk_mul_f32 v[36:37], v[38:39], v[36:37]
	s_nop 0
	v_cvt_pk_bf16_f32 v35, v36, v37
	global_store_dwordx2 v[66:67], v[34:35], off offset:48 sc1
	v_pk_mul_f32 v[34:35], v[40:41], v[68:69] op_sel_hi:[1,0]
	v_pk_mul_f32 v[36:37], v[54:55], v[68:69] op_sel_hi:[1,0]
	s_waitcnt vmcnt(1)
	v_pk_mul_f32 v[34:35], v[34:35], v[42:43]
	v_pk_mul_f32 v[36:37], v[36:37], v[44:45]
	v_cvt_pk_bf16_f32 v34, v34, v35
	v_cvt_pk_bf16_f32 v35, v36, v37
	global_store_dwordx2 v[66:67], v[34:35], off offset:112 sc1

; __device__ __forceinline__ void store4bf(bf16_t* p, f32x4 v) { u32x2 w; w.x = cvt_pk_bf16(v[0], v[1]); w.y = cvt_pk_bf16(v[2], v[3]); *(u32x2*)p = w; }
; __device__ __forceinline__ float sum32(float v) { return v + xhalf(v); }
; template <int MODE>
; __device__ __forceinline__ void attn_item(const Params& P, int layer, int b, int h, int map, int qb) {
;     ...
;   const float la = sum32(sa.l), ia = 1.0f / la;
;   if (qvalid) {
;     const int row = meta ? NREAL + 16 * b + e_q : b * SEQ + (e_q - 64);
;     if (MODE == 1) {
;     } else {
;       const int ycol = MODE == 0 ? h * 64 : 640 + h * 64;
;       bf16_t* yp = (bf16_t*)(ws + WS_HN) + (size_t)row * DM + ycol + 4 * hh;
; #pragma unroll
;       for (int g = 0; g < 4; ++g) {
;         store4bf(yp + 8 * g, (f32x4){sa.o0[4 * g] * ia, sa.o0[4 * g + 1] * ia, sa.o0[4 * g + 2] * ia, sa.o0[4 * g + 3] * ia});
;         store4bf(yp + 32 + 8 * g, (f32x4){sa.o1[4 * g] * ia, sa.o1[4 * g + 1] * ia, sa.o1[4 * g + 2] * ia, sa.o1[4 * g + 3] * ia});
;       }
;     }
.LBB0_1322:
	v_mov_b32_e32 v0, v210
	s_nop 0
	v_lshlrev_b32_e32 v0, 2, v0
	v_xor_b32_e32 v0, 0x80, v0
	ds_bpermute_b32 v0, v0, v190
	s_and_saveexec_b64 s[2:3], s[24:25]
	s_cbranch_execz .LBB0_1238
	s_waitcnt lgkmcnt(0)
	v_add_f32_e32 v0, v190, v0
	v_div_scale_f32 v2, s[4:5], v0, v0, 1.0
	v_rcp_f32_e32 v3, v2
	v_div_scale_f32 v4, vcc, 1.0, v0, 1.0
	v_fma_f32 v5, -v2, v3, 1.0
	v_fmac_f32_e32 v3, v5, v3
	v_mul_f32_e32 v5, v4, v3
	v_fma_f32 v6, -v2, v5, v4
	v_fmac_f32_e32 v5, v6, v3
	v_fma_f32 v2, -v2, v5, v4
	v_div_fmas_f32 v2, v2, v3, v5
	v_div_fixup_f32 v0, v2, v0, 1.0
	v_add_u32_e32 v2, s74, v151
	v_ashrrev_i32_e32 v3, 31, v2
	v_lshlrev_b64 v[2:3], 11, v[2:3]
	v_lshl_add_u64 v[2:3], s[10:11], 0, v[2:3]
	v_mov_b32_e32 v151, v1
	v_pk_mul_f32 v[4:5], v[32:33], v[0:1] op_sel_hi:[1,0]
	v_pk_mul_f32 v[6:7], v[34:35], v[0:1] op_sel_hi:[1,0]
	v_lshl_add_u64 v[2:3], v[2:3], 0, v[150:151]
	v_cvt_pk_bf16_f32 v4, v4, v5
	v_cvt_pk_bf16_f32 v5, v6, v7
	global_store_dwordx2 v[2:3], v[4:5], off sc1
	v_pk_mul_f32 v[4:5], v[16:17], v[0:1] op_sel_hi:[1,0]
	v_pk_mul_f32 v[6:7], v[18:19], v[0:1] op_sel_hi:[1,0]
	v_cvt_pk_bf16_f32 v4, v4, v5
	v_cvt_pk_bf16_f32 v5, v6, v7
	global_store_dwordx2 v[2:3], v[4:5], off offset:64 sc1
	v_pk_mul_f32 v[4:5], v[36:37], v[0:1] op_sel_hi:[1,0]
	v_pk_mul_f32 v[6:7], v[38:39], v[0:1] op_sel_hi:[1,0]
	v_cvt_pk_bf16_f32 v4, v4, v5
	v_cvt_pk_bf16_f32 v5, v6, v7
	global_store_dwordx2 v[2:3], v[4:5], off offset:16 sc1
	v_pk_mul_f32 v[4:5], v[20:21], v[0:1] op_sel_hi:[1,0]
	v_pk_mul_f32 v[6:7], v[22:23], v[0:1] op_sel_hi:[1,0]
	v_cvt_pk_bf16_f32 v4, v4, v5
	v_cvt_pk_bf16_f32 v5, v6, v7
	global_store_dwordx2 v[2:3], v[4:5], off offset:80 sc1
	v_pk_mul_f32 v[4:5], v[40:41], v[0:1] op_sel_hi:[1,0]
	v_pk_mul_f32 v[6:7], v[42:43], v[0:1] op_sel_hi:[1,0]
	v_cvt_pk_bf16_f32 v4, v4, v5
	v_cvt_pk_bf16_f32 v5, v6, v7
	global_store_dwordx2 v[2:3], v[4:5], off offset:32 sc1
	v_pk_mul_f32 v[4:5], v[24:25], v[0:1] op_sel_hi:[1,0]
	v_pk_mul_f32 v[6:7], v[26:27], v[0:1] op_sel_hi:[1,0]
	v_cvt_pk_bf16_f32 v4, v4, v5
	v_cvt_pk_bf16_f32 v5, v6, v7
	global_store_dwordx2 v[2:3], v[4:5], off offset:96 sc1
	v_pk_mul_f32 v[4:5], v[44:45], v[0:1] op_sel_hi:[1,0]
	v_pk_mul_f32 v[6:7], v[46:47], v[0:1] op_sel_hi:[1,0]
	v_cvt_pk_bf16_f32 v4, v4, v5
	v_cvt_pk_bf16_f32 v5, v6, v7
	global_store_dwordx2 v[2:3], v[4:5], off offset:48 sc1
	v_pk_mul_f32 v[4:5], v[28:29], v[0:1] op_sel_hi:[1,0]
	v_pk_mul_f32 v[6:7], v[30:31], v[0:1] op_sel_hi:[1,0]
	v_cvt_pk_bf16_f32 v4, v4, v5
	v_cvt_pk_bf16_f32 v5, v6, v7
	global_store_dwordx2 v[2:3], v[4:5], off offset:112 sc1
	s_branch .LBB0_1238

; #define LAS __attribute__((address_space(3)))
; __device__ __forceinline__ void store4bf(bf16_t* p, f32x4 v) { u32x2 w; w.x = cvt_pk_bf16(v[0], v[1]); w.y = cvt_pk_bf16(v[2], v[3]); *(u32x2*)p = w; }
; __device__ __forceinline__ float sum32(float v) { return v + xhalf(v); }
; template <int MODE>
; __device__ __forceinline__ void attn_item(const Params& P, int layer, int b, int h, int map, int qb) {
;     ...
;   const float la = sum32(sa.l), ia = 1.0f / la;
;   if (qvalid) {
;     const int row = meta ? NREAL + 16 * b + e_q : b * SEQ + (e_q - 64);
;     if (MODE == 1) {
;     } else {
;       const int ycol = MODE == 0 ? h * 64 : 640 + h * 64;
;       bf16_t* yp = (bf16_t*)(ws + WS_HN) + (size_t)row * DM + ycol + 4 * hh;
; #pragma unroll
;       for (int g = 0; g < 4; ++g) {
;         store4bf(yp + 8 * g, (f32x4){sa.o0[4 * g] * ia, sa.o0[4 * g + 1] * ia, sa.o0[4 * g + 2] * ia, sa.o0[4 * g + 3] * ia});
;         store4bf(yp + 32 + 8 * g, (f32x4){sa.o1[4 * g] * ia, sa.o1[4 * g + 1] * ia, sa.o1[4 * g + 2] * ia, sa.o1[4 * g + 3] * ia});
;       }
;     }
;   }
;   if (MODE == 1) {
;     LAS float* stash = (LAS float*)(lds + 4 * KBUF + 4 * VBUF + 1024) + (size_t)w * 32 * 64 + lane;
;     if (map == 0) {
; #pragma unroll
;       for (int i = 0; i < 16; ++i) { stash[i * 64] = sa.o0[i] * ia; stash[(16 + i) * 64] = sa.o1[i] * ia; }
;     } else {
;       const float lam = ((const float*)(ws + WS_CTL))[8 + layer], li = layer == 0 ? 0.2f : 0.35550906f, ib = lam * ia;
;       f32x16 y0, y1; float ss = 0.f;
; #pragma unroll
;       for (int i = 0; i < 16; ++i) { y0[i] = stash[i * 64] - sa.o0[i] * ib; y1[i] = stash[(16 + i) * 64] - sa.o1[i] * ib; ss += y0[i] * y0[i] + y1[i] * y1[i]; }
;       ss = sum32(ss);
.LBB0_1370:
	ds_write_b128 v111, v[66:69] offset:10240
	ds_write_b128 v114, v[70:73] offset:38912
	ds_write_b128 v111, v[66:69] offset:15360
	ds_write_b128 v114, v[70:73] offset:48128
	v_mov_b32_e32 v66, v210
	s_waitcnt lgkmcnt(0)
	s_barrier
	v_and_b32_e32 v74, 63, v110
	v_lshlrev_b32_e32 v66, 2, v66
	v_xor_b32_e32 v66, 0x80, v66
	ds_bpermute_b32 v66, v66, v102
	s_xor_b64 s[2:3], s[34:35], -1
	s_waitcnt lgkmcnt(0)
	v_add_f32_e32 v66, v102, v66
	v_div_scale_f32 v67, s[4:5], v66, v66, 1.0
	v_rcp_f32_e32 v68, v67
	s_lshl_b32 s4, s40, 7
	s_and_b32 s4, s4, 0xffffe000
	s_add_i32 s4, s4, 0
	v_fma_f32 v69, -v67, v68, 1.0
	v_fmac_f32_e32 v68, v69, v68
	v_div_scale_f32 v69, vcc, 1.0, v66, 1.0
	v_mul_f32_e32 v70, v69, v68
	v_fma_f32 v71, -v67, v70, v69
	v_fmac_f32_e32 v70, v71, v68
	v_fma_f32 v67, -v67, v70, v69
	v_div_fmas_f32 v67, v67, v68, v70
	v_lshl_add_u32 v103, v74, 2, s4
	v_div_fixup_f32 v101, v67, v66, 1.0
	v_add_u32_e32 v102, 0xe400, v103
	s_andn2_b64 vcc, exec, s[2:3]
	s_mov_b64 s[4:5], -1
	s_cbranch_vccnz .LBB0_1374
	global_load_dword v66, v1, s[52:53] offset:32
	s_waitcnt vmcnt(0)
	v_mul_f32_e32 v86, v101, v66
	ds_read2st64_b32 v[66:67], v103 offset0:228 offset1:229
	ds_read2st64_b32 v[68:69], v103 offset0:244 offset1:245
	s_waitcnt lgkmcnt(1)
	v_pk_fma_f32 v[94:95], v[50:51], v[86:87], v[66:67] op_sel_hi:[1,0,1] neg_lo:[1,0,0] neg_hi:[1,0,0]
	s_waitcnt lgkmcnt(0)
	v_pk_fma_f32 v[66:67], v[34:35], v[86:87], v[68:69] op_sel_hi:[1,0,1] neg_lo:[1,0,0] neg_hi:[1,0,0]
	s_nop 0
	v_pk_mul_f32 v[68:69], v[66:67], v[66:67]
	s_nop 0
	v_pk_fma_f32 v[98:99], v[94:95], v[94:95], v[68:69]
	ds_read2st64_b32 v[68:69], v103 offset0:230 offset1:231
	ds_read2st64_b32 v[70:71], v103 offset0:246 offset1:247
	v_add_f32_e32 v98, v98, v99
	v_mov_b32_e32 v99, v210
	s_waitcnt lgkmcnt(1)
	v_pk_fma_f32 v[96:97], v[52:53], v[86:87], v[68:69] op_sel_hi:[1,0,1] neg_lo:[1,0,0] neg_hi:[1,0,0]
	s_waitcnt lgkmcnt(0)
	v_pk_fma_f32 v[74:75], v[36:37], v[86:87], v[70:71] op_sel_hi:[1,0,1] neg_lo:[1,0,0] neg_hi:[1,0,0]
	s_nop 0
	v_pk_mul_f32 v[68:69], v[74:75], v[74:75]
	s_nop 0
	v_pk_fma_f32 v[104:105], v[96:97], v[96:97], v[68:69]
	ds_read2st64_b32 v[68:69], v103 offset0:232 offset1:233
	ds_read2st64_b32 v[70:71], v103 offset0:248 offset1:249
	v_add_f32_e32 v98, v98, v104
	v_add_f32_e32 v98, v98, v105
	s_waitcnt lgkmcnt(1)
	v_pk_fma_f32 v[76:77], v[54:55], v[86:87], v[68:69] op_sel_hi:[1,0,1] neg_lo:[1,0,0] neg_hi:[1,0,0]
	s_waitcnt lgkmcnt(0)
	v_pk_fma_f32 v[68:69], v[38:39], v[86:87], v[70:71] op_sel_hi:[1,0,1] neg_lo:[1,0,0] neg_hi:[1,0,0]
	s_nop 0
	v_pk_mul_f32 v[70:71], v[68:69], v[68:69]
	s_nop 0
	v_pk_fma_f32 v[110:111], v[76:77], v[76:77], v[70:71]
	ds_read2st64_b32 v[70:71], v103 offset0:234 offset1:235
	ds_read2st64_b32 v[72:73], v103 offset0:250 offset1:251
	v_add_f32_e32 v98, v98, v110
	v_add_f32_e32 v98, v98, v111
	s_waitcnt lgkmcnt(1)
	v_pk_fma_f32 v[88:89], v[56:57], v[86:87], v[70:71] op_sel_hi:[1,0,1] neg_lo:[1,0,0] neg_hi:[1,0,0]
	s_waitcnt lgkmcnt(0)
	v_pk_fma_f32 v[78:79], v[40:41], v[86:87], v[72:73] op_sel_hi:[1,0,1] neg_lo:[1,0,0] neg_hi:[1,0,0]
	s_nop 0
	v_pk_mul_f32 v[70:71], v[78:79], v[78:79]
	s_nop 0
	v_pk_fma_f32 v[114:115], v[88:89], v[88:89], v[70:71]
	ds_read2st64_b32 v[70:71], v103 offset0:236 offset1:237
	ds_read2st64_b32 v[72:73], v103 offset0:252 offset1:253
	v_add_f32_e32 v98, v98, v114
	v_add_f32_e32 v98, v98, v115
	s_waitcnt lgkmcnt(1)
	v_pk_fma_f32 v[80:81], v[58:59], v[86:87], v[70:71] op_sel_hi:[1,0,1] neg_lo:[1,0,0] neg_hi:[1,0,0]
	s_waitcnt lgkmcnt(0)
	v_pk_fma_f32 v[70:71], v[42:43], v[86:87], v[72:73] op_sel_hi:[1,0,1] neg_lo:[1,0,0] neg_hi:[1,0,0]
	s_nop 0
	v_pk_mul_f32 v[72:73], v[70:71], v[70:71]
	s_nop 0
	v_pk_fma_f32 v[116:117], v[80:81], v[80:81], v[72:73]
	ds_read2st64_b32 v[72:73], v103 offset0:238 offset1:239
	ds_read2st64_b32 v[82:83], v103 offset0:254 offset1:255
	v_add_f32_e32 v98, v98, v116
	v_add_f32_e32 v98, v98, v117
	s_waitcnt lgkmcnt(1)
	v_pk_fma_f32 v[90:91], v[60:61], v[86:87], v[72:73] op_sel_hi:[1,0,1] neg_lo:[1,0,0] neg_hi:[1,0,0]
	s_waitcnt lgkmcnt(0)
	v_pk_fma_f32 v[82:83], v[44:45], v[86:87], v[82:83] op_sel_hi:[1,0,1] neg_lo:[1,0,0] neg_hi:[1,0,0]
	s_nop 0
	v_pk_mul_f32 v[72:73], v[82:83], v[82:83]
	s_nop 0
	v_pk_fma_f32 v[118:119], v[90:91], v[90:91], v[72:73]
	ds_read2st64_b32 v[72:73], v103 offset0:240 offset1:241
	ds_read2st64_b32 v[92:93], v102 offset0:28 offset1:29
	v_add_f32_e32 v98, v98, v118
	v_add_f32_e32 v98, v98, v119
	s_waitcnt lgkmcnt(1)
	v_pk_fma_f32 v[84:85], v[62:63], v[86:87], v[72:73] op_sel_hi:[1,0,1] neg_lo:[1,0,0] neg_hi:[1,0,0]
	s_waitcnt lgkmcnt(0)
	v_pk_fma_f32 v[72:73], v[46:47], v[86:87], v[92:93] op_sel_hi:[1,0,1] neg_lo:[1,0,0] neg_hi:[1,0,0]
	s_nop 0
	v_pk_mul_f32 v[92:93], v[72:73], v[72:73]
	s_nop 0
	v_pk_fma_f32 v[120:121], v[84:85], v[84:85], v[92:93]
	ds_read2st64_b32 v[92:93], v103 offset0:242 offset1:243
	ds_read2st64_b32 v[122:123], v102 offset0:30 offset1:31
	v_add_f32_e32 v98, v98, v120
	v_add_f32_e32 v98, v98, v121
	s_waitcnt lgkmcnt(1)
	v_pk_fma_f32 v[92:93], v[64:65], v[86:87], v[92:93] op_sel_hi:[1,0,1] neg_lo:[1,0,0] neg_hi:[1,0,0]
	s_waitcnt lgkmcnt(0)
	v_pk_fma_f32 v[86:87], v[48:49], v[86:87], v[122:123] op_sel_hi:[1,0,1] neg_lo:[1,0,0] neg_hi:[1,0,0]
	v_lshlrev_b32_e32 v99, 2, v99
	v_pk_mul_f32 v[122:123], v[86:87], v[86:87]
	v_xor_b32_e32 v99, 0x80, v99
	v_pk_fma_f32 v[122:123], v[92:93], v[92:93], v[122:123]
	s_nop 0
	v_add_f32_e32 v98, v98, v122
	v_add_f32_e32 v98, v98, v123
	ds_bpermute_b32 v99, v99, v98
	s_and_saveexec_b64 s[4:5], s[24:25]
	s_cbranch_execz .LBB0_1373
; __device__ __forceinline__ void store4bf(bf16_t* p, f32x4 v) { u32x2 w; w.x = cvt_pk_bf16(v[0], v[1]); w.y = cvt_pk_bf16(v[2], v[3]); *(u32x2*)p = w; }
; __device__ __forceinline__ float sum32(float v) { return v + xhalf(v); }
; template <int MODE>
; __device__ __forceinline__ void attn_item(const Params& P, int layer, int b, int h, int map, int qb) {
;     ...
;       ss = sum32(ss);
;       const float rs = rsqrtf(ss * (1.0f / 64.0f) + 1e-6f) * (1.0f - li);
;       const float* sg = P.subln + layer * 64 + 4 * hh;
;       if (qvalid) {
;         const int row = meta ? NREAL + 16 * b + e_q : b * SEQ + (e_q - 64);
;         bf16_t* yp = (bf16_t*)(ws + WS_HN) + (size_t)row * DM + 384 + h * 64 + 4 * hh;
; #pragma unroll
;         for (int g = 0; g < 4; ++g) {
;           const f32x4 g0 = *(const f32x4*)(sg + 8 * g), g1 = *(const f32x4*)(sg + 32 + 8 * g);
;           store4bf(yp + 8 * g, (f32x4){y0[4 * g] * rs * g0[0], y0[4 * g + 1] * rs * g0[1], y0[4 * g + 2] * rs * g0[2], y0[4 * g + 3] * rs * g0[3]});
;           store4bf(yp + 32 + 8 * g, (f32x4){y1[4 * g] * rs * g1[0], y1[4 * g + 1] * rs * g1[1], y1[4 * g + 2] * rs * g1[2], y1[4 * g + 3] * rs * g1[3]});
;         }
;       }
	s_waitcnt lgkmcnt(0)
	v_add_f32_e32 v98, v98, v99
	v_fmamk_f32 v98, v98, 0x3c800000, v154
	v_cmp_gt_f32_e32 vcc, s46, v98
	v_mul_f32_e32 v99, 0x4b800000, v98
	v_readlane_b32 s8, v253, 16
	v_cndmask_b32_e32 v98, v98, v99, vcc
	v_rsq_f32_e32 v98, v98
	v_readlane_b32 s14, v253, 22
	v_readlane_b32 s15, v253, 23
	s_mov_b64 s[6:7], 0xb082300
	v_mul_f32_e32 v99, 0x45800000, v98
	v_cndmask_b32_e32 v98, v98, v99, vcc
	v_mul_f32_e32 v100, v220, v98
	v_or_b32_e32 v98, s23, v109
	v_mov_b32_e32 v99, v1
	v_lshlrev_b64 v[98:99], 11, v[98:99]
	v_lshl_add_u64 v[98:99], s[14:15], 0, v[98:99]
	v_lshl_add_u64 v[98:99], v[98:99], 0, s[90:91]
	v_mov_b32_e32 v109, v1
	v_lshl_add_u64 v[104:105], v[98:99], 0, v[108:109]
	global_load_dwordx4 v[108:111], v0, s[56:57]
	global_load_dwordx4 v[114:117], v0, s[56:57] offset:128
	v_pk_mul_f32 v[94:95], v[94:95], v[100:101] op_sel_hi:[1,0]
	v_pk_mul_f32 v[96:97], v[96:97], v[100:101] op_sel_hi:[1,0]
	v_pk_mul_f32 v[66:67], v[66:67], v[100:101] op_sel_hi:[1,0]
	v_pk_mul_f32 v[74:75], v[74:75], v[100:101] op_sel_hi:[1,0]
	v_lshl_add_u64 v[98:99], v[104:105], 0, s[6:7]
	v_readlane_b32 s9, v253, 17
	v_readlane_b32 s10, v253, 18
	v_readlane_b32 s11, v253, 19
	v_readlane_b32 s12, v253, 20
	v_readlane_b32 s13, v253, 21
	s_waitcnt vmcnt(1)
	v_pk_mul_f32 v[94:95], v[94:95], v[108:109]
	v_pk_mul_f32 v[96:97], v[96:97], v[110:111]
	v_cvt_pk_bf16_f32 v94, v94, v95
	v_cvt_pk_bf16_f32 v95, v96, v97
	v_add_co_u32_e32 v96, vcc, s88, v104
	s_waitcnt vmcnt(0)
	v_pk_mul_f32 v[66:67], v[66:67], v[114:115]
	v_pk_mul_f32 v[74:75], v[74:75], v[116:117]
	v_addc_co_u32_e32 v97, vcc, 0, v105, vcc
	v_cvt_pk_bf16_f32 v66, v66, v67
	v_cvt_pk_bf16_f32 v67, v74, v75
	global_store_dwordx2 v[96:97], v[94:95], off offset:768 sc1
	global_store_dwordx2 v[98:99], v[66:67], off offset:64 sc1
	global_load_dwordx4 v[94:97], v0, s[56:57] offset:32
	s_nop 0
	global_load_dwordx4 v[108:111], v0, s[56:57] offset:160
	v_pk_mul_f32 v[66:67], v[76:77], v[100:101] op_sel_hi:[1,0]
	v_pk_mul_f32 v[74:75], v[88:89], v[100:101] op_sel_hi:[1,0]
	s_waitcnt vmcnt(1)
	v_pk_mul_f32 v[66:67], v[66:67], v[94:95]
	v_pk_mul_f32 v[74:75], v[74:75], v[96:97]
	v_cvt_pk_bf16_f32 v66, v66, v67
	v_cvt_pk_bf16_f32 v67, v74, v75
	global_store_dwordx2 v[98:99], v[66:67], off offset:16 sc1
	v_pk_mul_f32 v[66:67], v[68:69], v[100:101] op_sel_hi:[1,0]
	v_pk_mul_f32 v[68:69], v[78:79], v[100:101] op_sel_hi:[1,0]
	s_waitcnt vmcnt(1)
	v_pk_mul_f32 v[66:67], v[66:67], v[108:109]
	v_pk_mul_f32 v[68:69], v[68:69], v[110:111]
	v_cvt_pk_bf16_f32 v66, v66, v67
	v_cvt_pk_bf16_f32 v67, v68, v69
	global_store_dwordx2 v[98:99], v[66:67], off offset:80 sc1
	global_load_dwordx4 v[66:69], v0, s[56:57] offset:64
	s_nop 0
	global_load_dwordx4 v[74:77], v0, s[56:57] offset:192
	v_pk_mul_f32 v[78:79], v[80:81], v[100:101] op_sel_hi:[1,0]
	s_waitcnt vmcnt(1)
	v_pk_mul_f32 v[66:67], v[78:79], v[66:67]
	v_pk_mul_f32 v[78:79], v[90:91], v[100:101] op_sel_hi:[1,0]
	v_cvt_pk_bf16_f32 v66, v66, v67
	v_pk_mul_f32 v[68:69], v[78:79], v[68:69]
	s_nop 0
	v_cvt_pk_bf16_f32 v67, v68, v69
	global_store_dwordx2 v[98:99], v[66:67], off offset:32 sc1
	v_pk_mul_f32 v[66:67], v[70:71], v[100:101] op_sel_hi:[1,0]
	v_pk_mul_f32 v[68:69], v[82:83], v[100:101] op_sel_hi:[1,0]
	s_waitcnt vmcnt(1)
	v_pk_mul_f32 v[66:67], v[66:67], v[74:75]
	v_pk_mul_f32 v[68:69], v[68:69], v[76:77]
	v_cvt_pk_bf16_f32 v66, v66, v67
	v_cvt_pk_bf16_f32 v67, v68, v69
	global_store_dwordx2 v[98:99], v[66:67], off offset:96 sc1
	global_load_dwordx4 v[66:69], v0, s[56:57] offset:96
	s_nop 0
	global_load_dwordx4 v[74:77], v0, s[56:57] offset:224
	v_pk_mul_f32 v[70:71], v[84:85], v[100:101] op_sel_hi:[1,0]
	s_waitcnt vmcnt(1)
	v_pk_mul_f32 v[66:67], v[70:71], v[66:67]
	v_pk_mul_f32 v[70:71], v[92:93], v[100:101] op_sel_hi:[1,0]
	v_cvt_pk_bf16_f32 v66, v66, v67
	v_pk_mul_f32 v[68:69], v[70:71], v[68:69]
	s_nop 0
	v_cvt_pk_bf16_f32 v67, v68, v69
	global_store_dwordx2 v[98:99], v[66:67], off offset:48 sc1
	v_pk_mul_f32 v[66:67], v[72:73], v[100:101] op_sel_hi:[1,0]
	v_pk_mul_f32 v[68:69], v[86:87], v[100:101] op_sel_hi:[1,0]
	s_waitcnt vmcnt(1)
	v_pk_mul_f32 v[66:67], v[66:67], v[74:75]
	v_pk_mul_f32 v[68:69], v[68:69], v[76:77]
	v_cvt_pk_bf16_f32 v66, v66, v67
	v_cvt_pk_bf16_f32 v67, v68, v69
	global_store_dwordx2 v[98:99], v[66:67], off offset:112 sc1

; __device__ __forceinline__ void store4bf(bf16_t* p, f32x4 v) { u32x2 w; w.x = cvt_pk_bf16(v[0], v[1]); w.y = cvt_pk_bf16(v[2], v[3]); *(u32x2*)p = w; }
; __device__ __forceinline__ float sum32(float v) { return v + xhalf(v); }
; template <int MODE>
; __device__ __forceinline__ void attn_item(const Params& P, int layer, int b, int h, int map, int qb) {
;     ...
;   const float la = sum32(sa.l), ia = 1.0f / la;
;   if (qvalid) {
;     const int row = meta ? NREAL + 16 * b + e_q : b * SEQ + (e_q - 64);
;     if (MODE == 1) {
;     } else {
;       const int ycol = MODE == 0 ? h * 64 : 640 + h * 64;
;       bf16_t* yp = (bf16_t*)(ws + WS_HN) + (size_t)row * DM + ycol + 4 * hh;
; #pragma unroll
;       for (int g = 0; g < 4; ++g) {
;         store4bf(yp + 8 * g, (f32x4){sa.o0[4 * g] * ia, sa.o0[4 * g + 1] * ia, sa.o0[4 * g + 2] * ia, sa.o0[4 * g + 3] * ia});
;         store4bf(yp + 32 + 8 * g, (f32x4){sa.o1[4 * g] * ia, sa.o1[4 * g + 1] * ia, sa.o1[4 * g + 2] * ia, sa.o1[4 * g + 3] * ia});
;       }
;     }
.LBB0_1430:
	s_and_saveexec_b64 s[2:3], s[18:19]
	s_xor_b64 s[2:3], exec, s[2:3]
	s_cbranch_execz .LBB0_1326
	s_waitcnt vmcnt(2) lgkmcnt(0)
	v_div_scale_f32 v0, s[4:5], v113, v113, 1.0
	v_rcp_f32_e32 v34, v0
	v_div_scale_f32 v35, vcc, 1.0, v113, 1.0
	v_fma_f32 v36, -v0, v34, 1.0
	v_fmac_f32_e32 v34, v36, v34
	v_mul_f32_e32 v36, v35, v34
	v_fma_f32 v37, -v0, v36, v35
	v_fmac_f32_e32 v36, v37, v34
	v_fma_f32 v0, -v0, v36, v35
	v_div_fmas_f32 v0, v0, v34, v36
	v_div_fixup_f32 v0, v0, v113, 1.0
	v_lshlrev_b32_e32 v34, 3, v166
	v_mov_b32_e32 v35, v1
	v_pk_mul_f32 v[2:3], v[0:1], v[2:3] op_sel_hi:[0,1]
	v_pk_mul_f32 v[4:5], v[0:1], v[4:5] op_sel_hi:[0,1]
	v_lshl_add_u64 v[34:35], v[106:107], 0, v[34:35]
	v_cvt_pk_bf16_f32 v2, v2, v3
	v_cvt_pk_bf16_f32 v3, v4, v5
	global_store_dwordx2 v[34:35], v[2:3], off offset:64 sc1
	v_pk_mul_f32 v[2:3], v[22:23], v[0:1] op_sel_hi:[1,0]
	v_pk_mul_f32 v[4:5], v[24:25], v[0:1] op_sel_hi:[1,0]
	v_cvt_pk_bf16_f32 v2, v2, v3
	v_cvt_pk_bf16_f32 v3, v4, v5
	global_store_dwordx2 v[34:35], v[2:3], off offset:16 sc1
	v_pk_mul_f32 v[2:3], v[0:1], v[6:7] op_sel_hi:[0,1]
	v_pk_mul_f32 v[4:5], v[0:1], v[8:9] op_sel_hi:[0,1]
	v_cvt_pk_bf16_f32 v2, v2, v3
	v_cvt_pk_bf16_f32 v3, v4, v5
	global_store_dwordx2 v[34:35], v[2:3], off offset:80 sc1
	v_pk_mul_f32 v[2:3], v[26:27], v[0:1] op_sel_hi:[1,0]
	v_pk_mul_f32 v[4:5], v[28:29], v[0:1] op_sel_hi:[1,0]
	v_cvt_pk_bf16_f32 v2, v2, v3
	v_cvt_pk_bf16_f32 v3, v4, v5
	global_store_dwordx2 v[34:35], v[2:3], off offset:32 sc1
	v_pk_mul_f32 v[2:3], v[0:1], v[10:11] op_sel_hi:[0,1]
	v_pk_mul_f32 v[4:5], v[0:1], v[12:13] op_sel_hi:[0,1]
	v_cvt_pk_bf16_f32 v2, v2, v3
	v_cvt_pk_bf16_f32 v3, v4, v5
	global_store_dwordx2 v[34:35], v[2:3], off offset:96 sc1
	v_pk_mul_f32 v[2:3], v[30:31], v[0:1] op_sel_hi:[1,0]
	v_pk_mul_f32 v[4:5], v[32:33], v[0:1] op_sel_hi:[1,0]
	v_cvt_pk_bf16_f32 v2, v2, v3
	v_cvt_pk_bf16_f32 v3, v4, v5
	v_pk_mul_f32 v[18:19], v[18:19], v[0:1] op_sel_hi:[1,0]
	v_pk_mul_f32 v[20:21], v[20:21], v[0:1] op_sel_hi:[1,0]
	global_store_dwordx2 v[34:35], v[2:3], off offset:48 sc1
	v_pk_mul_f32 v[2:3], v[0:1], v[14:15] op_sel_hi:[0,1]
	v_pk_mul_f32 v[4:5], v[0:1], v[16:17] op_sel_hi:[0,1]
	v_cvt_pk_bf16_f32 v18, v18, v19
	v_cvt_pk_bf16_f32 v19, v20, v21
	v_cvt_pk_bf16_f32 v2, v2, v3
	v_cvt_pk_bf16_f32 v3, v4, v5
	global_store_dwordx2 v[34:35], v[18:19], off sc1
	global_store_dwordx2 v[34:35], v[2:3], off offset:112 sc1
	s_branch .LBB0_1326
